# win: next tile k-tiles 1,2 prefetched into dead acc regs before the epilogue store ladder, both LDS buffers filled in the tile prologue, two peeled k-iterations without vmcnt dependence on the stores
# baseline (speedup 1.0000x reference)
; #define ZERO_ACC8(acc, NJ_)                             \
;   _Pragma("unroll") for (int i_ = 0; i_ < 8; ++i_)      \
;   _Pragma("unroll") for (int j_ = 0; j_ < (NJ_); ++j_) { acc[i_][j_] = (f32x4){0.f, 0.f, 0.f, 0.f}; }
; template <int MI, int NJ> ...
;     ...
;   if (!pre) G8LOADP(Ag, Bg);
;   G8STORE(0);
;   {
;     const u16* ga_ = (1 < nk) ? Ag + 64 : Ag + nAoff;
;     const u16* gb_ = (1 < nk) ? Bg + 64 : Bg + nBoff;
;     G8LOADP(ga_, gb_);
;   }
;   __syncthreads();
; __device__ __forceinline__ void phase_win(const Params& p, int part, u16* smem, volatile LAS unsigned* vb_) {
;     ...
;   auto ntile = [&](int nl_) { return (part == 0) ? ((nl_ < 6) ? nl_ : (14 + nl_ - 6)) : ((nl_ < 8) ? (6 + nl_) : (20 + nl_ - 8)); };
;   for (int lt = vb >> 3; lt < 8 * NT; lt += step) {
;     const int nl = lt >> 3, mt = (vb & 7) * 8 + (lt & 7);
;     const int nt = ntile(nl);
;     const int ltn = (lt + step < 8 * NT) ? lt + step : lt;
;     const int nmt = (vb & 7) * 8 + (ltn & 7), nnt = ntile(ltn >> 3);
;     u16* dstA; u16* dstB; int ldA, ldB;
;     {
;       const int ct = nt * 2;
;       if (ct < 12) { dstA = (u16*)(p.ws + OFF_UCONV) + ct * 128; ldA = 1536; }
;       else if (ct < 28) { dstA = (u16*)(p.ws + OFF_UHG) + (ct - 12) * 128; ldA = 2048; }
;       else if (ct < 40) { dstA = (u16*)(p.ws + OFF_UNSA) + (ct - 28) * 128; ldA = 1536; }
;       else { dstA = (u16*)(p.ws + OFF_UMG) + (ct - 40) * 128; ldA = 3072; }
;       dstB = dstA + 128; ldB = ldA;
;     }
;     f32x4 acc[8][4];
;     ZERO_ACC8(acc, 4);
;     gemm8<8, 4>(acc, G8REGS_ARGS, pre, H, 1024, W, 1024, 0, 1024, mt * 256, nt * 256, nmt * 256, nnt * 256, 0, smem, tid);
.LBB0_467:
	s_and_b32 s11, s38, 7
	s_or_b32 s10, s11, s23
	s_lshl_b32 s10, s10, 8
	v_add_u32_e32 v34, s10, v184
	v_ashrrev_i32_e32 v35, 31, v34
	v_lshlrev_b64 v[34:35], 11, v[34:35]
	v_lshl_add_u64 v[180:181], v[176:177], 0, v[34:35]
	v_add_u32_e32 v34, s20, v184
	v_ashrrev_i32_e32 v35, 31, v34
	v_lshlrev_b64 v[34:35], 11, v[34:35]
	s_xor_b64 s[12:13], s[12:13], -1
	s_andn2_b64 vcc, exec, s[12:13]
	v_lshl_add_u64 v[182:183], v[178:179], 0, v[34:35]
	v_readfirstlane_b32 s62, v180
	v_readfirstlane_b32 s63, v181
	v_readfirstlane_b32 s64, v182
	v_readfirstlane_b32 s65, v183
	s_nop 4
	s_cbranch_vccnz .Lwin_pre
	global_load_dwordx4 v[10:13], v234, s[62:63]
	global_load_dwordx4 v[2:5], v235, s[62:63]
	global_load_dwordx4 v[6:9], v236, s[62:63]
	global_load_dwordx4 v[18:21], v237, s[62:63]
	global_load_dwordx4 v[14:17], v234, s[64:65]
	global_load_dwordx4 v[22:25], v235, s[64:65]
	global_load_dwordx4 v[26:29], v236, s[64:65]
	global_load_dwordx4 v[30:33], v237, s[64:65]
	s_waitcnt vmcnt(5)
	ds_write_b128 v185, v[10:13]
	ds_write_b128 v185, v[2:5] offset:8192
	ds_write_b128 v185, v[6:9] offset:16384
	s_waitcnt vmcnt(3)
	ds_write_b128 v185, v[18:21] offset:24576
	ds_write_b128 v186, v[14:17]
	s_waitcnt vmcnt(2)
	ds_write_b128 v186, v[22:25] offset:8192
	s_waitcnt vmcnt(1)
	ds_write_b128 v186, v[26:29] offset:16384
	s_waitcnt vmcnt(0)
	ds_write_b128 v186, v[30:33] offset:24576
	global_load_dwordx4 v[10:13], v234, s[62:63] offset:128
	global_load_dwordx4 v[2:5], v235, s[62:63] offset:128
	global_load_dwordx4 v[6:9], v236, s[62:63] offset:128
	global_load_dwordx4 v[18:21], v237, s[62:63] offset:128
	global_load_dwordx4 v[14:17], v234, s[64:65] offset:128
	global_load_dwordx4 v[22:25], v235, s[64:65] offset:128
	global_load_dwordx4 v[26:29], v236, s[64:65] offset:128
	global_load_dwordx4 v[30:33], v237, s[64:65] offset:128
	s_mov_b32 s68, 0
	s_branch .Lwin_join
.Lwin_pre:
	s_waitcnt vmcnt(32)
	ds_write_b128 v185, v[10:13]
	ds_write_b128 v185, v[2:5] offset:8192
	ds_write_b128 v185, v[6:9] offset:16384
	ds_write_b128 v185, v[18:21] offset:24576
	ds_write_b128 v186, v[14:17]
	ds_write_b128 v186, v[22:25] offset:8192
	ds_write_b128 v186, v[26:29] offset:16384
	ds_write_b128 v186, v[30:33] offset:24576
	s_waitcnt vmcnt(24)
	ds_write_b128 v185, v[98:101] offset:32768
	ds_write_b128 v185, v[102:105] offset:40960
	ds_write_b128 v185, v[106:109] offset:49152
	ds_write_b128 v185, v[110:113] offset:57344
	ds_write_b128 v186, v[114:117] offset:32768
	ds_write_b128 v186, v[118:121] offset:40960
	ds_write_b128 v186, v[122:125] offset:49152
	ds_write_b128 v186, v[126:129] offset:57344
	s_waitcnt vmcnt(16) lgkmcnt(0)
	v_mov_b64_e32 v[10:11], v[130:131]
	v_mov_b64_e32 v[12:13], v[132:133]
	v_mov_b64_e32 v[2:3], v[134:135]
	v_mov_b64_e32 v[4:5], v[136:137]
	v_mov_b64_e32 v[6:7], v[138:139]
	v_mov_b64_e32 v[8:9], v[140:141]
	v_mov_b64_e32 v[18:19], v[142:143]
	v_mov_b64_e32 v[20:21], v[144:145]
	v_mov_b64_e32 v[14:15], v[146:147]
	v_mov_b64_e32 v[16:17], v[148:149]
	v_mov_b64_e32 v[22:23], v[150:151]
	v_mov_b64_e32 v[24:25], v[152:153]
	v_mov_b64_e32 v[26:27], v[154:155]
	v_mov_b64_e32 v[28:29], v[156:157]
	v_mov_b64_e32 v[30:31], v[158:159]
	v_mov_b64_e32 v[32:33], v[160:161]
	s_mov_b32 s68, 1
.Lwin_join:
	s_and_b32 s12, s39, 7
	s_sub_i32 s11, s12, s11
	s_lshl_b32 s12, s11, 8
	s_sub_i32 s11, s46, s37
	s_lshl_b32 s20, s11, 8
	s_ashr_i32 s13, s12, 31
	s_ashr_i32 s21, s20, 31
	v_mov_b32_e32 v34, 0
	s_lshl_b64 s[12:13], s[12:13], 10
	s_lshl_b64 s[46:47], s[20:21], 10
	s_mov_b32 s11, 0
	s_mov_b64 s[20:21], 0x80
	s_mov_b32 s37, 0
	v_mov_b32_e32 v35, v34
	v_mov_b32_e32 v36, v34
	v_mov_b32_e32 v37, v34
	v_mov_b32_e32 v38, v34
	v_mov_b32_e32 v39, v34
	v_mov_b32_e32 v40, v34
	v_mov_b32_e32 v41, v34
	v_mov_b32_e32 v42, v34
	v_mov_b32_e32 v43, v34
	v_mov_b32_e32 v44, v34
	v_mov_b32_e32 v45, v34
	v_mov_b32_e32 v46, v34
	v_mov_b32_e32 v47, v34
	v_mov_b32_e32 v48, v34
	v_mov_b32_e32 v49, v34
	v_mov_b32_e32 v50, v34
	v_mov_b32_e32 v51, v34
	v_mov_b32_e32 v52, v34
	v_mov_b32_e32 v53, v34
	v_mov_b32_e32 v54, v34
	v_mov_b32_e32 v55, v34
	v_mov_b32_e32 v56, v34
	v_mov_b32_e32 v57, v34
	v_mov_b32_e32 v58, v34
	v_mov_b32_e32 v59, v34
	v_mov_b32_e32 v60, v34
	v_mov_b32_e32 v61, v34
	v_mov_b32_e32 v62, v34
	v_mov_b32_e32 v63, v34
	v_mov_b32_e32 v64, v34
	v_mov_b32_e32 v65, v34
	v_mov_b32_e32 v66, v34
	v_mov_b32_e32 v67, v34
	v_mov_b32_e32 v68, v34
	v_mov_b32_e32 v69, v34
	v_mov_b32_e32 v70, v34
	v_mov_b32_e32 v71, v34
	v_mov_b32_e32 v72, v34
	v_mov_b32_e32 v73, v34
	v_mov_b32_e32 v74, v34
	v_mov_b32_e32 v75, v34
	v_mov_b32_e32 v76, v34
	v_mov_b32_e32 v77, v34
	v_mov_b32_e32 v78, v34
	v_mov_b32_e32 v79, v34
	v_mov_b32_e32 v80, v34
	v_mov_b32_e32 v81, v34
	v_mov_b32_e32 v82, v34
	v_mov_b32_e32 v83, v34
	v_mov_b32_e32 v84, v34
	v_mov_b32_e32 v85, v34
	v_mov_b32_e32 v86, v34
	v_mov_b32_e32 v87, v34
	v_mov_b32_e32 v88, v34
	v_mov_b32_e32 v89, v34
	v_mov_b32_e32 v90, v34
	v_mov_b32_e32 v91, v34
	v_mov_b32_e32 v92, v34
	v_mov_b32_e32 v93, v34
	v_mov_b32_e32 v94, v34
	v_mov_b32_e32 v95, v34
	v_mov_b32_e32 v96, v34
	v_mov_b32_e32 v97, v34
	v_mov_b32_e32 v98, v34
	v_mov_b32_e32 v99, v34
	v_mov_b32_e32 v100, v34
	v_mov_b32_e32 v101, v34
	v_mov_b32_e32 v102, v34
	v_mov_b32_e32 v103, v34
	v_mov_b32_e32 v104, v34
	v_mov_b32_e32 v105, v34
	v_mov_b32_e32 v106, v34
	v_mov_b32_e32 v107, v34
	v_mov_b32_e32 v108, v34
	v_mov_b32_e32 v109, v34
	v_mov_b32_e32 v110, v34
	v_mov_b32_e32 v111, v34
	v_mov_b32_e32 v112, v34
	v_mov_b32_e32 v113, v34
	v_mov_b32_e32 v114, v34
	v_mov_b32_e32 v115, v34
	v_mov_b32_e32 v116, v34
	v_mov_b32_e32 v117, v34
	v_mov_b32_e32 v118, v34
	v_mov_b32_e32 v119, v34
	v_mov_b32_e32 v120, v34
	v_mov_b32_e32 v121, v34
	v_mov_b32_e32 v122, v34
	v_mov_b32_e32 v123, v34
	v_mov_b32_e32 v124, v34
	v_mov_b32_e32 v125, v34
	v_mov_b32_e32 v126, v34
	v_mov_b32_e32 v127, v34
	v_mov_b32_e32 v128, v34
	v_mov_b32_e32 v129, v34
	v_mov_b32_e32 v130, v34
	v_mov_b32_e32 v131, v34
	v_mov_b32_e32 v132, v34
	v_mov_b32_e32 v133, v34
	v_mov_b32_e32 v134, v34
	v_mov_b32_e32 v135, v34
	v_mov_b32_e32 v136, v34
	v_mov_b32_e32 v137, v34
	v_mov_b32_e32 v138, v34
	v_mov_b32_e32 v139, v34
	v_mov_b32_e32 v140, v34
	v_mov_b32_e32 v141, v34
	v_mov_b32_e32 v142, v34
	v_mov_b32_e32 v143, v34
	v_mov_b32_e32 v144, v34
	v_mov_b32_e32 v145, v34
	v_mov_b32_e32 v146, v34
	v_mov_b32_e32 v147, v34
	v_mov_b32_e32 v148, v34
	v_mov_b32_e32 v149, v34
	v_mov_b32_e32 v150, v34
	v_mov_b32_e32 v151, v34
	v_mov_b32_e32 v152, v34
	v_mov_b32_e32 v153, v34
	v_mov_b32_e32 v154, v34
	v_mov_b32_e32 v155, v34
	v_mov_b32_e32 v156, v34
	v_mov_b32_e32 v157, v34
	v_mov_b32_e32 v158, v34
	v_mov_b32_e32 v159, v34
	v_mov_b32_e32 v160, v34
	v_mov_b32_e32 v161, v34
	s_waitcnt lgkmcnt(0)
	s_barrier
; template <int MI, int NJ> ...
;     ...
;   for (int kt = 0; kt < nk; ++kt) {
;     const int buf = kt & 1;
;     {
;       G8STORE(buf ^ 1);
;       const u16* ga_ = (kt + 2 < nk) ? Ag + (kt + 2) * 64 : Ag + nAoff;
;       const u16* gb_ = (kt + 2 < nk) ? Bg + (kt + 2) * 64 : Bg + nBoff;
;       G8LOADP(ga_, gb_);
;     }
;     __builtin_amdgcn_sched_barrier(0);
;     __builtin_amdgcn_s_setprio(1);
;     const u16* a = ra_ + buf * AROWS * 64;
;     const u16* b = rb_ + buf * BROWS * 64;
; #pragma unroll
;     for (int ks = 0; ks < 2; ++ks) {
;       const u16* a_ = ks ? a + dsw : a;
;       const u16* b_ = ks ? b + dsw : b;
;       bf16x8 bfr[NJ];
; #pragma unroll
;       for (int j = 0; j < NJ; ++j) bfr[j] = *(const bf16x8*)(b_ + j * 16 * 64);
; #pragma unroll
;       for (int ih = 0; ih < MI / 4; ++ih) {
;         bf16x8 af[4];
; #pragma unroll
;         for (int i = 0; i < 4; ++i) af[i] = *(const bf16x8*)(a_ + (ih * 4 + i) * 16 * 64);
; #pragma unroll
;         for (int i = 0; i < 4; ++i)
; #pragma unroll
;           for (int j = 0; j < NJ; ++j) acc[ih * 4 + i][j] = mfma16(af[i], bfr[j], acc[ih * 4 + i][j]);
;       }
;     }
;     __builtin_amdgcn_s_setprio(0);
;     __builtin_amdgcn_sched_barrier(0);
;     __syncthreads();
	s_and_b32 s38, s11, 0x4000
	s_xor_b32 s39, s38, 0x4000
	s_lshl_b32 s39, s39, 1
	v_add_u32_e32 v228, s39, v185
	v_add_u32_e32 v229, s39, v186
	s_cmp_lt_u32 s37, 14
	s_cselect_b32 s49, s21, s13
	s_cselect_b32 s48, s20, s12
	s_cselect_b32 s51, s21, s47
	s_cselect_b32 s50, s20, s46
	s_lshl_b64 s[48:49], s[48:49], 1
	s_lshl_b64 s[50:51], s[50:51], 1
	s_add_u32 s52, s62, s48
	s_addc_u32 s53, s63, s49
	s_add_u32 s66, s64, s50
	s_addc_u32 s67, s65, s51
	s_lshl_b32 s38, s38, 1
	v_add_u32_e32 v0, s38, v187
	v_add_u32_e32 v191, s38, v188
	ds_read_b128 v[166:169], v191
	ds_read_b128 v[162:165], v0
	ds_read_b128 v[170:173], v191 offset:2048
	ds_read_b128 v[192:195], v191 offset:4096
	ds_read_b128 v[196:199], v191 offset:6144
	ds_read_b128 v[204:207], v0 offset:2048
	ds_read_b128 v[208:211], v0 offset:4096
	ds_read_b128 v[238:241], v0 offset:6144
	v_add_u32_e32 v191, v191, v190
	s_cmp_eq_u32 s68, 0
	s_cbranch_scc1 .LBB0_470
	s_setprio 1
	s_waitcnt lgkmcnt(6)
	v_mfma_f32_16x16x32_bf16 v[158:161], v[166:169], v[162:165], v[158:161]
	s_waitcnt lgkmcnt(5)
	v_mfma_f32_16x16x32_bf16 v[154:157], v[170:173], v[162:165], v[154:157]
	s_waitcnt lgkmcnt(4)
	v_mfma_f32_16x16x32_bf16 v[150:153], v[192:195], v[162:165], v[150:153]
	s_waitcnt lgkmcnt(3)
	v_mfma_f32_16x16x32_bf16 v[146:149], v[196:199], v[162:165], v[146:149]
	ds_read_b128 v[162:165], v0 offset:8192
	s_waitcnt lgkmcnt(3)
	v_mfma_f32_16x16x32_bf16 v[142:145], v[166:169], v[204:207], v[142:145]
	v_mfma_f32_16x16x32_bf16 v[138:141], v[170:173], v[204:207], v[138:141]
	v_mfma_f32_16x16x32_bf16 v[134:137], v[192:195], v[204:207], v[134:137]
	v_mfma_f32_16x16x32_bf16 v[130:133], v[196:199], v[204:207], v[130:133]
	ds_read_b128 v[204:207], v0 offset:10240
	s_waitcnt lgkmcnt(3)
	v_mfma_f32_16x16x32_bf16 v[126:129], v[166:169], v[208:211], v[126:129]
	v_mfma_f32_16x16x32_bf16 v[122:125], v[170:173], v[208:211], v[122:125]
	v_mfma_f32_16x16x32_bf16 v[118:121], v[192:195], v[208:211], v[118:121]
	v_mfma_f32_16x16x32_bf16 v[114:117], v[196:199], v[208:211], v[114:117]
	ds_read_b128 v[208:211], v0 offset:12288
	ds_read_b128 v[212:215], v191
	ds_read_b128 v[216:219], v191 offset:2048
	s_waitcnt lgkmcnt(5)
	v_mfma_f32_16x16x32_bf16 v[110:113], v[166:169], v[238:241], v[110:113]
	v_mfma_f32_16x16x32_bf16 v[106:109], v[170:173], v[238:241], v[106:109]
	v_mfma_f32_16x16x32_bf16 v[102:105], v[192:195], v[238:241], v[102:105]
	v_mfma_f32_16x16x32_bf16 v[98:101], v[196:199], v[238:241], v[98:101]
	ds_read_b128 v[238:241], v0 offset:14336
	ds_read_b128 v[220:223], v191 offset:4096
	ds_read_b128 v[224:227], v191 offset:6144
	s_waitcnt lgkmcnt(7)
	v_mfma_f32_16x16x32_bf16 v[94:97], v[166:169], v[162:165], v[94:97]
	v_mfma_f32_16x16x32_bf16 v[90:93], v[170:173], v[162:165], v[90:93]
	v_mfma_f32_16x16x32_bf16 v[86:89], v[192:195], v[162:165], v[86:89]
	v_mfma_f32_16x16x32_bf16 v[82:85], v[196:199], v[162:165], v[82:85]
	v_add_u32_e32 v0, v0, v190
	ds_read_b128 v[162:165], v0
	s_waitcnt lgkmcnt(7)
	v_mfma_f32_16x16x32_bf16 v[78:81], v[166:169], v[204:207], v[78:81]
	v_mfma_f32_16x16x32_bf16 v[74:77], v[170:173], v[204:207], v[74:77]
	v_mfma_f32_16x16x32_bf16 v[70:73], v[192:195], v[204:207], v[70:73]
	v_mfma_f32_16x16x32_bf16 v[66:69], v[196:199], v[204:207], v[66:69]
	ds_read_b128 v[204:207], v0 offset:2048
	s_waitcnt lgkmcnt(7)
	v_mfma_f32_16x16x32_bf16 v[62:65], v[166:169], v[208:211], v[62:65]
	v_mfma_f32_16x16x32_bf16 v[58:61], v[170:173], v[208:211], v[58:61]
	v_mfma_f32_16x16x32_bf16 v[54:57], v[192:195], v[208:211], v[54:57]
	v_mfma_f32_16x16x32_bf16 v[50:53], v[196:199], v[208:211], v[50:53]
	ds_read_b128 v[208:211], v0 offset:4096
	s_waitcnt lgkmcnt(5)
	v_mfma_f32_16x16x32_bf16 v[46:49], v[166:169], v[238:241], v[46:49]
	v_mfma_f32_16x16x32_bf16 v[42:45], v[170:173], v[238:241], v[42:45]
	v_mfma_f32_16x16x32_bf16 v[38:41], v[192:195], v[238:241], v[38:41]
	v_mfma_f32_16x16x32_bf16 v[34:37], v[196:199], v[238:241], v[34:37]
	ds_read_b128 v[238:241], v0 offset:6144
	s_waitcnt lgkmcnt(3)
	v_mfma_f32_16x16x32_bf16 v[158:161], v[212:215], v[162:165], v[158:161]
	v_mfma_f32_16x16x32_bf16 v[154:157], v[216:219], v[162:165], v[154:157]
	v_mfma_f32_16x16x32_bf16 v[150:153], v[220:223], v[162:165], v[150:153]
	v_mfma_f32_16x16x32_bf16 v[146:149], v[224:227], v[162:165], v[146:149]
	ds_read_b128 v[162:165], v0 offset:8192
	s_waitcnt lgkmcnt(3)
	v_mfma_f32_16x16x32_bf16 v[142:145], v[212:215], v[204:207], v[142:145]
	v_mfma_f32_16x16x32_bf16 v[138:141], v[216:219], v[204:207], v[138:141]
	v_mfma_f32_16x16x32_bf16 v[134:137], v[220:223], v[204:207], v[134:137]
	v_mfma_f32_16x16x32_bf16 v[130:133], v[224:227], v[204:207], v[130:133]
	ds_read_b128 v[204:207], v0 offset:10240
	s_waitcnt lgkmcnt(3)
	v_mfma_f32_16x16x32_bf16 v[126:129], v[212:215], v[208:211], v[126:129]
	v_mfma_f32_16x16x32_bf16 v[122:125], v[216:219], v[208:211], v[122:125]
	v_mfma_f32_16x16x32_bf16 v[118:121], v[220:223], v[208:211], v[118:121]
	v_mfma_f32_16x16x32_bf16 v[114:117], v[224:227], v[208:211], v[114:117]
	ds_read_b128 v[208:211], v0 offset:12288
	s_waitcnt lgkmcnt(3)
	v_mfma_f32_16x16x32_bf16 v[110:113], v[212:215], v[238:241], v[110:113]
	v_mfma_f32_16x16x32_bf16 v[106:109], v[216:219], v[238:241], v[106:109]
	v_mfma_f32_16x16x32_bf16 v[102:105], v[220:223], v[238:241], v[102:105]
	v_mfma_f32_16x16x32_bf16 v[98:101], v[224:227], v[238:241], v[98:101]
	ds_read_b128 v[238:241], v0 offset:14336
	s_waitcnt lgkmcnt(3)
	v_mfma_f32_16x16x32_bf16 v[94:97], v[212:215], v[162:165], v[94:97]
	v_mfma_f32_16x16x32_bf16 v[90:93], v[216:219], v[162:165], v[90:93]
	v_mfma_f32_16x16x32_bf16 v[86:89], v[220:223], v[162:165], v[86:89]
	v_mfma_f32_16x16x32_bf16 v[82:85], v[224:227], v[162:165], v[82:85]
	s_waitcnt lgkmcnt(0)
	s_setprio 0
	s_barrier
; template <int MI, int NJ> ...
;     ...
;   for (int kt = 0; kt < nk; ++kt) {
;     const int buf = kt & 1;
;     {
;       G8STORE(buf ^ 1);
;       const u16* ga_ = (kt + 2 < nk) ? Ag + (kt + 2) * 64 : Ag + nAoff;
;       const u16* gb_ = (kt + 2 < nk) ? Bg + (kt + 2) * 64 : Bg + nBoff;
;       G8LOADP(ga_, gb_);
;     }
;     __builtin_amdgcn_sched_barrier(0);
;     __builtin_amdgcn_s_setprio(1);
;     const u16* a = ra_ + buf * AROWS * 64;
;     const u16* b = rb_ + buf * BROWS * 64;
; #pragma unroll
;     for (int ks = 0; ks < 2; ++ks) {
;       const u16* a_ = ks ? a + dsw : a;
;       const u16* b_ = ks ? b + dsw : b;
;       bf16x8 bfr[NJ];
; #pragma unroll
;       for (int j = 0; j < NJ; ++j) bfr[j] = *(const bf16x8*)(b_ + j * 16 * 64);
; #pragma unroll
;       for (int ih = 0; ih < MI / 4; ++ih) {
;         bf16x8 af[4];
; #pragma unroll
;         for (int i = 0; i < 4; ++i) af[i] = *(const bf16x8*)(a_ + (ih * 4 + i) * 16 * 64);
; #pragma unroll
;         for (int i = 0; i < 4; ++i)
; #pragma unroll
;           for (int j = 0; j < NJ; ++j) acc[ih * 4 + i][j] = mfma16(af[i], bfr[j], acc[ih * 4 + i][j]);
;       }
;     }
;     __builtin_amdgcn_s_setprio(0);
;     __builtin_amdgcn_sched_barrier(0);
;     __syncthreads();
	s_add_i32 s37, s37, 1
	s_add_u32 s20, s20, 64
	s_addc_u32 s21, s21, 0
	s_addk_i32 s11, 0x4000
	s_and_b32 s38, s11, 0x4000
	s_xor_b32 s39, s38, 0x4000
	s_lshl_b32 s39, s39, 1
	v_add_u32_e32 v228, s39, v185
	v_add_u32_e32 v229, s39, v186
	s_cmp_lt_u32 s37, 14
	s_cselect_b32 s49, s21, s13
	s_cselect_b32 s48, s20, s12
	s_cselect_b32 s51, s21, s47
	s_cselect_b32 s50, s20, s46
	s_lshl_b64 s[48:49], s[48:49], 1
	s_lshl_b64 s[50:51], s[50:51], 1
	s_add_u32 s52, s62, s48
	s_addc_u32 s53, s63, s49
	s_add_u32 s66, s64, s50
	s_addc_u32 s67, s65, s51
	s_lshl_b32 s38, s38, 1
	v_add_u32_e32 v0, s38, v187
	v_add_u32_e32 v191, s38, v188
	s_setprio 1
	ds_read_b128 v[166:169], v191
	ds_read_b128 v[162:165], v0
	ds_read_b128 v[170:173], v191 offset:2048
	ds_read_b128 v[192:195], v191 offset:4096
	ds_read_b128 v[196:199], v191 offset:6144
	v_mfma_f32_16x16x32_bf16 v[78:81], v[212:215], v[204:207], v[78:81]
	v_mfma_f32_16x16x32_bf16 v[74:77], v[216:219], v[204:207], v[74:77]
	v_mfma_f32_16x16x32_bf16 v[70:73], v[220:223], v[204:207], v[70:73]
	v_mfma_f32_16x16x32_bf16 v[66:69], v[224:227], v[204:207], v[66:69]
	ds_read_b128 v[204:207], v0 offset:2048
	v_mfma_f32_16x16x32_bf16 v[62:65], v[212:215], v[208:211], v[62:65]
	v_mfma_f32_16x16x32_bf16 v[58:61], v[216:219], v[208:211], v[58:61]
	v_mfma_f32_16x16x32_bf16 v[54:57], v[220:223], v[208:211], v[54:57]
	v_mfma_f32_16x16x32_bf16 v[50:53], v[224:227], v[208:211], v[50:53]
	ds_read_b128 v[208:211], v0 offset:4096
	v_mfma_f32_16x16x32_bf16 v[46:49], v[212:215], v[238:241], v[46:49]
	v_mfma_f32_16x16x32_bf16 v[42:45], v[216:219], v[238:241], v[42:45]
	v_mfma_f32_16x16x32_bf16 v[38:41], v[220:223], v[238:241], v[38:41]
	v_mfma_f32_16x16x32_bf16 v[34:37], v[224:227], v[238:241], v[34:37]
	ds_read_b128 v[238:241], v0 offset:6144
	v_add_u32_e32 v191, v191, v190
	s_setprio 0
	s_cmpk_lg_i32 s20, 0x480
	s_setprio 1
	s_waitcnt lgkmcnt(6)
	v_mfma_f32_16x16x32_bf16 v[158:161], v[166:169], v[162:165], v[158:161]
	s_waitcnt lgkmcnt(5)
	v_mfma_f32_16x16x32_bf16 v[154:157], v[170:173], v[162:165], v[154:157]
	s_waitcnt lgkmcnt(4)
	v_mfma_f32_16x16x32_bf16 v[150:153], v[192:195], v[162:165], v[150:153]
	s_waitcnt lgkmcnt(3)
	v_mfma_f32_16x16x32_bf16 v[146:149], v[196:199], v[162:165], v[146:149]
	ds_read_b128 v[162:165], v0 offset:8192
	s_waitcnt lgkmcnt(3)
	v_mfma_f32_16x16x32_bf16 v[142:145], v[166:169], v[204:207], v[142:145]
	v_mfma_f32_16x16x32_bf16 v[138:141], v[170:173], v[204:207], v[138:141]
	v_mfma_f32_16x16x32_bf16 v[134:137], v[192:195], v[204:207], v[134:137]
	v_mfma_f32_16x16x32_bf16 v[130:133], v[196:199], v[204:207], v[130:133]
	ds_read_b128 v[204:207], v0 offset:10240
	s_waitcnt lgkmcnt(3)
	v_mfma_f32_16x16x32_bf16 v[126:129], v[166:169], v[208:211], v[126:129]
	v_mfma_f32_16x16x32_bf16 v[122:125], v[170:173], v[208:211], v[122:125]
	v_mfma_f32_16x16x32_bf16 v[118:121], v[192:195], v[208:211], v[118:121]
	v_mfma_f32_16x16x32_bf16 v[114:117], v[196:199], v[208:211], v[114:117]
	ds_read_b128 v[208:211], v0 offset:12288
	ds_read_b128 v[212:215], v191
	ds_read_b128 v[216:219], v191 offset:2048
	s_waitcnt lgkmcnt(5)
	v_mfma_f32_16x16x32_bf16 v[110:113], v[166:169], v[238:241], v[110:113]
	v_mfma_f32_16x16x32_bf16 v[106:109], v[170:173], v[238:241], v[106:109]
	v_mfma_f32_16x16x32_bf16 v[102:105], v[192:195], v[238:241], v[102:105]
	v_mfma_f32_16x16x32_bf16 v[98:101], v[196:199], v[238:241], v[98:101]
	ds_read_b128 v[238:241], v0 offset:14336
	ds_read_b128 v[220:223], v191 offset:4096
	ds_read_b128 v[224:227], v191 offset:6144
	s_waitcnt lgkmcnt(7)
	v_mfma_f32_16x16x32_bf16 v[94:97], v[166:169], v[162:165], v[94:97]
	v_mfma_f32_16x16x32_bf16 v[90:93], v[170:173], v[162:165], v[90:93]
	v_mfma_f32_16x16x32_bf16 v[86:89], v[192:195], v[162:165], v[86:89]
	v_mfma_f32_16x16x32_bf16 v[82:85], v[196:199], v[162:165], v[82:85]
	v_add_u32_e32 v0, v0, v190
	ds_read_b128 v[162:165], v0
	ds_write_b128 v228, v[10:13]
	global_load_dwordx4 v[10:13], v234, s[52:53]
	s_waitcnt lgkmcnt(8)
	v_mfma_f32_16x16x32_bf16 v[78:81], v[166:169], v[204:207], v[78:81]
	v_mfma_f32_16x16x32_bf16 v[74:77], v[170:173], v[204:207], v[74:77]
	v_mfma_f32_16x16x32_bf16 v[70:73], v[192:195], v[204:207], v[70:73]
	v_mfma_f32_16x16x32_bf16 v[66:69], v[196:199], v[204:207], v[66:69]
	ds_read_b128 v[204:207], v0 offset:2048
	ds_write_b128 v228, v[2:5] offset:8192
	global_load_dwordx4 v[2:5], v235, s[52:53]
	s_waitcnt lgkmcnt(9)
	v_mfma_f32_16x16x32_bf16 v[62:65], v[166:169], v[208:211], v[62:65]
	v_mfma_f32_16x16x32_bf16 v[58:61], v[170:173], v[208:211], v[58:61]
	v_mfma_f32_16x16x32_bf16 v[54:57], v[192:195], v[208:211], v[54:57]
	v_mfma_f32_16x16x32_bf16 v[50:53], v[196:199], v[208:211], v[50:53]
	ds_read_b128 v[208:211], v0 offset:4096
	ds_write_b128 v228, v[6:9] offset:16384
	global_load_dwordx4 v[6:9], v236, s[52:53]
	s_waitcnt lgkmcnt(8)
	v_mfma_f32_16x16x32_bf16 v[46:49], v[166:169], v[238:241], v[46:49]
	v_mfma_f32_16x16x32_bf16 v[42:45], v[170:173], v[238:241], v[42:45]
	v_mfma_f32_16x16x32_bf16 v[38:41], v[192:195], v[238:241], v[38:41]
	v_mfma_f32_16x16x32_bf16 v[34:37], v[196:199], v[238:241], v[34:37]
	ds_read_b128 v[238:241], v0 offset:6144
	ds_write_b128 v228, v[18:21] offset:24576
	global_load_dwordx4 v[18:21], v237, s[52:53]
	s_waitcnt lgkmcnt(7)
	v_mfma_f32_16x16x32_bf16 v[158:161], v[212:215], v[162:165], v[158:161]
	v_mfma_f32_16x16x32_bf16 v[154:157], v[216:219], v[162:165], v[154:157]
	v_mfma_f32_16x16x32_bf16 v[150:153], v[220:223], v[162:165], v[150:153]
	v_mfma_f32_16x16x32_bf16 v[146:149], v[224:227], v[162:165], v[146:149]
	ds_read_b128 v[162:165], v0 offset:8192
	ds_write_b128 v229, v[14:17]
	global_load_dwordx4 v[14:17], v234, s[66:67]
	s_waitcnt lgkmcnt(7)
; template <int MI, int NJ> ...
;     ...
;   for (int kt = 0; kt < nk; ++kt) {
;     const int buf = kt & 1;
;     {
;       G8STORE(buf ^ 1);
;       const u16* ga_ = (kt + 2 < nk) ? Ag + (kt + 2) * 64 : Ag + nAoff;
;       const u16* gb_ = (kt + 2 < nk) ? Bg + (kt + 2) * 64 : Bg + nBoff;
;       G8LOADP(ga_, gb_);
;     }
;     __builtin_amdgcn_sched_barrier(0);
;     __builtin_amdgcn_s_setprio(1);
;     const u16* a = ra_ + buf * AROWS * 64;
;     const u16* b = rb_ + buf * BROWS * 64;
; #pragma unroll
;     for (int ks = 0; ks < 2; ++ks) {
;       const u16* a_ = ks ? a + dsw : a;
;       const u16* b_ = ks ? b + dsw : b;
;       bf16x8 bfr[NJ];
; #pragma unroll
;       for (int j = 0; j < NJ; ++j) bfr[j] = *(const bf16x8*)(b_ + j * 16 * 64);
; #pragma unroll
;       for (int ih = 0; ih < MI / 4; ++ih) {
;         bf16x8 af[4];
; #pragma unroll
;         for (int i = 0; i < 4; ++i) af[i] = *(const bf16x8*)(a_ + (ih * 4 + i) * 16 * 64);
; #pragma unroll
;         for (int i = 0; i < 4; ++i)
; #pragma unroll
;           for (int j = 0; j < NJ; ++j) acc[ih * 4 + i][j] = mfma16(af[i], bfr[j], acc[ih * 4 + i][j]);
;       }
;     }
;     __builtin_amdgcn_s_setprio(0);
;     __builtin_amdgcn_sched_barrier(0);
;     __syncthreads();
	v_mfma_f32_16x16x32_bf16 v[142:145], v[212:215], v[204:207], v[142:145]
	v_mfma_f32_16x16x32_bf16 v[138:141], v[216:219], v[204:207], v[138:141]
	v_mfma_f32_16x16x32_bf16 v[134:137], v[220:223], v[204:207], v[134:137]
	v_mfma_f32_16x16x32_bf16 v[130:133], v[224:227], v[204:207], v[130:133]
	ds_read_b128 v[204:207], v0 offset:10240
	ds_write_b128 v229, v[22:25] offset:8192
	global_load_dwordx4 v[22:25], v235, s[66:67]
	s_waitcnt lgkmcnt(7)
	v_mfma_f32_16x16x32_bf16 v[126:129], v[212:215], v[208:211], v[126:129]
	v_mfma_f32_16x16x32_bf16 v[122:125], v[216:219], v[208:211], v[122:125]
	v_mfma_f32_16x16x32_bf16 v[118:121], v[220:223], v[208:211], v[118:121]
	v_mfma_f32_16x16x32_bf16 v[114:117], v[224:227], v[208:211], v[114:117]
	ds_read_b128 v[208:211], v0 offset:12288
	ds_write_b128 v229, v[26:29] offset:16384
	global_load_dwordx4 v[26:29], v236, s[66:67]
	s_waitcnt lgkmcnt(7)
	v_mfma_f32_16x16x32_bf16 v[110:113], v[212:215], v[238:241], v[110:113]
	v_mfma_f32_16x16x32_bf16 v[106:109], v[216:219], v[238:241], v[106:109]
	v_mfma_f32_16x16x32_bf16 v[102:105], v[220:223], v[238:241], v[102:105]
	v_mfma_f32_16x16x32_bf16 v[98:101], v[224:227], v[238:241], v[98:101]
	ds_read_b128 v[238:241], v0 offset:14336
	ds_write_b128 v229, v[30:33] offset:24576
	global_load_dwordx4 v[30:33], v237, s[66:67]
	s_waitcnt lgkmcnt(7)
	v_mfma_f32_16x16x32_bf16 v[94:97], v[212:215], v[162:165], v[94:97]
	v_mfma_f32_16x16x32_bf16 v[90:93], v[216:219], v[162:165], v[90:93]
	v_mfma_f32_16x16x32_bf16 v[86:89], v[220:223], v[162:165], v[86:89]
	v_mfma_f32_16x16x32_bf16 v[82:85], v[224:227], v[162:165], v[82:85]
	s_waitcnt lgkmcnt(0)
	s_setprio 0
	s_barrier
	s_add_i32 s37, s37, 1
	s_add_u32 s20, s20, 64
	s_addc_u32 s21, s21, 0
	s_addk_i32 s11, 0x4000
	s_and_b32 s38, s11, 0x4000
	s_xor_b32 s39, s38, 0x4000
	s_lshl_b32 s39, s39, 1
	v_add_u32_e32 v228, s39, v185
	v_add_u32_e32 v229, s39, v186
	s_cmp_lt_u32 s37, 14
	s_cselect_b32 s49, s21, s13
	s_cselect_b32 s48, s20, s12
	s_cselect_b32 s51, s21, s47
	s_cselect_b32 s50, s20, s46
	s_lshl_b64 s[48:49], s[48:49], 1
	s_lshl_b64 s[50:51], s[50:51], 1
	s_add_u32 s52, s62, s48
	s_addc_u32 s53, s63, s49
	s_add_u32 s66, s64, s50
	s_addc_u32 s67, s65, s51
	s_lshl_b32 s38, s38, 1
	v_add_u32_e32 v0, s38, v187
	v_add_u32_e32 v191, s38, v188
	s_setprio 1
	ds_read_b128 v[166:169], v191
	ds_read_b128 v[162:165], v0
	ds_read_b128 v[170:173], v191 offset:2048
	ds_read_b128 v[192:195], v191 offset:4096
	ds_read_b128 v[196:199], v191 offset:6144
	v_mfma_f32_16x16x32_bf16 v[78:81], v[212:215], v[204:207], v[78:81]
	v_mfma_f32_16x16x32_bf16 v[74:77], v[216:219], v[204:207], v[74:77]
	v_mfma_f32_16x16x32_bf16 v[70:73], v[220:223], v[204:207], v[70:73]
	v_mfma_f32_16x16x32_bf16 v[66:69], v[224:227], v[204:207], v[66:69]
	ds_read_b128 v[204:207], v0 offset:2048
	v_mfma_f32_16x16x32_bf16 v[62:65], v[212:215], v[208:211], v[62:65]
	v_mfma_f32_16x16x32_bf16 v[58:61], v[216:219], v[208:211], v[58:61]
	v_mfma_f32_16x16x32_bf16 v[54:57], v[220:223], v[208:211], v[54:57]
	v_mfma_f32_16x16x32_bf16 v[50:53], v[224:227], v[208:211], v[50:53]
	ds_read_b128 v[208:211], v0 offset:4096
	v_mfma_f32_16x16x32_bf16 v[46:49], v[212:215], v[238:241], v[46:49]
	v_mfma_f32_16x16x32_bf16 v[42:45], v[216:219], v[238:241], v[42:45]
	v_mfma_f32_16x16x32_bf16 v[38:41], v[220:223], v[238:241], v[38:41]
	v_mfma_f32_16x16x32_bf16 v[34:37], v[224:227], v[238:241], v[34:37]
	ds_read_b128 v[238:241], v0 offset:6144
	v_add_u32_e32 v191, v191, v190
	s_setprio 0
	s_cmpk_lg_i32 s20, 0x480
.LBB0_470:
	s_setprio 1
	s_waitcnt lgkmcnt(6)
	v_mfma_f32_16x16x32_bf16 v[158:161], v[166:169], v[162:165], v[158:161]
	s_waitcnt lgkmcnt(5)
	v_mfma_f32_16x16x32_bf16 v[154:157], v[170:173], v[162:165], v[154:157]
	s_waitcnt lgkmcnt(4)
	v_mfma_f32_16x16x32_bf16 v[150:153], v[192:195], v[162:165], v[150:153]
	s_waitcnt lgkmcnt(3)
	v_mfma_f32_16x16x32_bf16 v[146:149], v[196:199], v[162:165], v[146:149]
	ds_read_b128 v[162:165], v0 offset:8192
	s_waitcnt lgkmcnt(3)
	v_mfma_f32_16x16x32_bf16 v[142:145], v[166:169], v[204:207], v[142:145]
	v_mfma_f32_16x16x32_bf16 v[138:141], v[170:173], v[204:207], v[138:141]
	v_mfma_f32_16x16x32_bf16 v[134:137], v[192:195], v[204:207], v[134:137]
	v_mfma_f32_16x16x32_bf16 v[130:133], v[196:199], v[204:207], v[130:133]
	ds_read_b128 v[204:207], v0 offset:10240
	s_waitcnt lgkmcnt(3)
	v_mfma_f32_16x16x32_bf16 v[126:129], v[166:169], v[208:211], v[126:129]
	v_mfma_f32_16x16x32_bf16 v[122:125], v[170:173], v[208:211], v[122:125]
	v_mfma_f32_16x16x32_bf16 v[118:121], v[192:195], v[208:211], v[118:121]
	v_mfma_f32_16x16x32_bf16 v[114:117], v[196:199], v[208:211], v[114:117]
	ds_read_b128 v[208:211], v0 offset:12288
	ds_read_b128 v[212:215], v191
	ds_read_b128 v[216:219], v191 offset:2048
	s_waitcnt lgkmcnt(5)
	v_mfma_f32_16x16x32_bf16 v[110:113], v[166:169], v[238:241], v[110:113]
	v_mfma_f32_16x16x32_bf16 v[106:109], v[170:173], v[238:241], v[106:109]
	v_mfma_f32_16x16x32_bf16 v[102:105], v[192:195], v[238:241], v[102:105]
	v_mfma_f32_16x16x32_bf16 v[98:101], v[196:199], v[238:241], v[98:101]
	ds_read_b128 v[238:241], v0 offset:14336
	ds_read_b128 v[220:223], v191 offset:4096
	ds_read_b128 v[224:227], v191 offset:6144
	s_waitcnt lgkmcnt(7)
	v_mfma_f32_16x16x32_bf16 v[94:97], v[166:169], v[162:165], v[94:97]
	v_mfma_f32_16x16x32_bf16 v[90:93], v[170:173], v[162:165], v[90:93]
	v_mfma_f32_16x16x32_bf16 v[86:89], v[192:195], v[162:165], v[86:89]
	v_mfma_f32_16x16x32_bf16 v[82:85], v[196:199], v[162:165], v[82:85]
	v_add_u32_e32 v0, v0, v190
	ds_read_b128 v[162:165], v0
	s_waitcnt vmcnt(7)
	ds_write_b128 v228, v[10:13]
	global_load_dwordx4 v[10:13], v234, s[52:53]
	s_waitcnt lgkmcnt(8)
; template <int MI, int NJ> ...
;     ...
;   for (int kt = 0; kt < nk; ++kt) {
;     const int buf = kt & 1;
;     {
;       G8STORE(buf ^ 1);
;       const u16* ga_ = (kt + 2 < nk) ? Ag + (kt + 2) * 64 : Ag + nAoff;
;       const u16* gb_ = (kt + 2 < nk) ? Bg + (kt + 2) * 64 : Bg + nBoff;
;       G8LOADP(ga_, gb_);
;     }
;     __builtin_amdgcn_sched_barrier(0);
;     __builtin_amdgcn_s_setprio(1);
;     const u16* a = ra_ + buf * AROWS * 64;
;     const u16* b = rb_ + buf * BROWS * 64;
; #pragma unroll
;     for (int ks = 0; ks < 2; ++ks) {
;       const u16* a_ = ks ? a + dsw : a;
;       const u16* b_ = ks ? b + dsw : b;
;       bf16x8 bfr[NJ];
; #pragma unroll
;       for (int j = 0; j < NJ; ++j) bfr[j] = *(const bf16x8*)(b_ + j * 16 * 64);
; #pragma unroll
;       for (int ih = 0; ih < MI / 4; ++ih) {
;         bf16x8 af[4];
; #pragma unroll
;         for (int i = 0; i < 4; ++i) af[i] = *(const bf16x8*)(a_ + (ih * 4 + i) * 16 * 64);
; #pragma unroll
;         for (int i = 0; i < 4; ++i)
; #pragma unroll
;           for (int j = 0; j < NJ; ++j) acc[ih * 4 + i][j] = mfma16(af[i], bfr[j], acc[ih * 4 + i][j]);
;       }
;     }
;     __builtin_amdgcn_s_setprio(0);
;     __builtin_amdgcn_sched_barrier(0);
;     __syncthreads();
	v_mfma_f32_16x16x32_bf16 v[78:81], v[166:169], v[204:207], v[78:81]
	v_mfma_f32_16x16x32_bf16 v[74:77], v[170:173], v[204:207], v[74:77]
	v_mfma_f32_16x16x32_bf16 v[70:73], v[192:195], v[204:207], v[70:73]
	v_mfma_f32_16x16x32_bf16 v[66:69], v[196:199], v[204:207], v[66:69]
	ds_read_b128 v[204:207], v0 offset:2048
	s_waitcnt vmcnt(7)
	ds_write_b128 v228, v[2:5] offset:8192
	global_load_dwordx4 v[2:5], v235, s[52:53]
	s_waitcnt lgkmcnt(9)
	v_mfma_f32_16x16x32_bf16 v[62:65], v[166:169], v[208:211], v[62:65]
	v_mfma_f32_16x16x32_bf16 v[58:61], v[170:173], v[208:211], v[58:61]
	v_mfma_f32_16x16x32_bf16 v[54:57], v[192:195], v[208:211], v[54:57]
	v_mfma_f32_16x16x32_bf16 v[50:53], v[196:199], v[208:211], v[50:53]
	ds_read_b128 v[208:211], v0 offset:4096
	s_waitcnt vmcnt(7)
	ds_write_b128 v228, v[6:9] offset:16384
	global_load_dwordx4 v[6:9], v236, s[52:53]
	s_waitcnt lgkmcnt(8)
	v_mfma_f32_16x16x32_bf16 v[46:49], v[166:169], v[238:241], v[46:49]
	v_mfma_f32_16x16x32_bf16 v[42:45], v[170:173], v[238:241], v[42:45]
	v_mfma_f32_16x16x32_bf16 v[38:41], v[192:195], v[238:241], v[38:41]
	v_mfma_f32_16x16x32_bf16 v[34:37], v[196:199], v[238:241], v[34:37]
	ds_read_b128 v[238:241], v0 offset:6144
	s_waitcnt vmcnt(7)
	ds_write_b128 v228, v[18:21] offset:24576
	global_load_dwordx4 v[18:21], v237, s[52:53]
	s_waitcnt lgkmcnt(7)
	v_mfma_f32_16x16x32_bf16 v[158:161], v[212:215], v[162:165], v[158:161]
	v_mfma_f32_16x16x32_bf16 v[154:157], v[216:219], v[162:165], v[154:157]
	v_mfma_f32_16x16x32_bf16 v[150:153], v[220:223], v[162:165], v[150:153]
	v_mfma_f32_16x16x32_bf16 v[146:149], v[224:227], v[162:165], v[146:149]
	ds_read_b128 v[162:165], v0 offset:8192
	s_waitcnt vmcnt(7)
	ds_write_b128 v229, v[14:17]
	global_load_dwordx4 v[14:17], v234, s[66:67]
	s_waitcnt lgkmcnt(7)
	v_mfma_f32_16x16x32_bf16 v[142:145], v[212:215], v[204:207], v[142:145]
	v_mfma_f32_16x16x32_bf16 v[138:141], v[216:219], v[204:207], v[138:141]
	v_mfma_f32_16x16x32_bf16 v[134:137], v[220:223], v[204:207], v[134:137]
	v_mfma_f32_16x16x32_bf16 v[130:133], v[224:227], v[204:207], v[130:133]
	ds_read_b128 v[204:207], v0 offset:10240
	s_waitcnt vmcnt(7)
	ds_write_b128 v229, v[22:25] offset:8192
	global_load_dwordx4 v[22:25], v235, s[66:67]
	s_waitcnt lgkmcnt(7)
	v_mfma_f32_16x16x32_bf16 v[126:129], v[212:215], v[208:211], v[126:129]
	v_mfma_f32_16x16x32_bf16 v[122:125], v[216:219], v[208:211], v[122:125]
	v_mfma_f32_16x16x32_bf16 v[118:121], v[220:223], v[208:211], v[118:121]
	v_mfma_f32_16x16x32_bf16 v[114:117], v[224:227], v[208:211], v[114:117]
	ds_read_b128 v[208:211], v0 offset:12288
	s_waitcnt vmcnt(7)
	ds_write_b128 v229, v[26:29] offset:16384
	global_load_dwordx4 v[26:29], v236, s[66:67]
	s_waitcnt lgkmcnt(7)
	v_mfma_f32_16x16x32_bf16 v[110:113], v[212:215], v[238:241], v[110:113]
	v_mfma_f32_16x16x32_bf16 v[106:109], v[216:219], v[238:241], v[106:109]
	v_mfma_f32_16x16x32_bf16 v[102:105], v[220:223], v[238:241], v[102:105]
	v_mfma_f32_16x16x32_bf16 v[98:101], v[224:227], v[238:241], v[98:101]
	ds_read_b128 v[238:241], v0 offset:14336
	s_waitcnt vmcnt(7)
	ds_write_b128 v229, v[30:33] offset:24576
	global_load_dwordx4 v[30:33], v237, s[66:67]
	s_waitcnt lgkmcnt(7)
	v_mfma_f32_16x16x32_bf16 v[94:97], v[212:215], v[162:165], v[94:97]
	v_mfma_f32_16x16x32_bf16 v[90:93], v[216:219], v[162:165], v[90:93]
	v_mfma_f32_16x16x32_bf16 v[86:89], v[220:223], v[162:165], v[86:89]
	v_mfma_f32_16x16x32_bf16 v[82:85], v[224:227], v[162:165], v[82:85]
	s_waitcnt lgkmcnt(0)
	s_setprio 0
	s_barrier
	s_add_i32 s37, s37, 1
	s_add_u32 s20, s20, 64
	s_addc_u32 s21, s21, 0
	s_addk_i32 s11, 0x4000
	s_and_b32 s38, s11, 0x4000
	s_xor_b32 s39, s38, 0x4000
	s_lshl_b32 s39, s39, 1
	v_add_u32_e32 v228, s39, v185
	v_add_u32_e32 v229, s39, v186
	s_cmp_lt_u32 s37, 14
	s_cselect_b32 s49, s21, s13
	s_cselect_b32 s48, s20, s12
	s_cselect_b32 s51, s21, s47
	s_cselect_b32 s50, s20, s46
	s_lshl_b64 s[48:49], s[48:49], 1
	s_lshl_b64 s[50:51], s[50:51], 1
	s_add_u32 s52, s62, s48
	s_addc_u32 s53, s63, s49
	s_add_u32 s66, s64, s50
	s_addc_u32 s67, s65, s51
	s_lshl_b32 s38, s38, 1
	v_add_u32_e32 v0, s38, v187
	v_add_u32_e32 v191, s38, v188
	s_setprio 1
	ds_read_b128 v[166:169], v191
	ds_read_b128 v[162:165], v0
	ds_read_b128 v[170:173], v191 offset:2048
	ds_read_b128 v[192:195], v191 offset:4096
	ds_read_b128 v[196:199], v191 offset:6144
	v_mfma_f32_16x16x32_bf16 v[78:81], v[212:215], v[204:207], v[78:81]
	v_mfma_f32_16x16x32_bf16 v[74:77], v[216:219], v[204:207], v[74:77]
	v_mfma_f32_16x16x32_bf16 v[70:73], v[220:223], v[204:207], v[70:73]
	v_mfma_f32_16x16x32_bf16 v[66:69], v[224:227], v[204:207], v[66:69]
	ds_read_b128 v[204:207], v0 offset:2048
	v_mfma_f32_16x16x32_bf16 v[62:65], v[212:215], v[208:211], v[62:65]
	v_mfma_f32_16x16x32_bf16 v[58:61], v[216:219], v[208:211], v[58:61]
	v_mfma_f32_16x16x32_bf16 v[54:57], v[220:223], v[208:211], v[54:57]
	v_mfma_f32_16x16x32_bf16 v[50:53], v[224:227], v[208:211], v[50:53]
	ds_read_b128 v[208:211], v0 offset:4096
	v_mfma_f32_16x16x32_bf16 v[46:49], v[212:215], v[238:241], v[46:49]
	v_mfma_f32_16x16x32_bf16 v[42:45], v[216:219], v[238:241], v[42:45]
	v_mfma_f32_16x16x32_bf16 v[38:41], v[220:223], v[238:241], v[38:41]
	v_mfma_f32_16x16x32_bf16 v[34:37], v[224:227], v[238:241], v[34:37]
	ds_read_b128 v[238:241], v0 offset:6144
	v_add_u32_e32 v191, v191, v190
	s_setprio 0
	s_cmpk_lg_i32 s20, 0x480
	s_cbranch_scc1 .LBB0_470
; #define RTID opaque_tid()
; __device__ __forceinline__ void phase_win(const Params& p, int part, u16* smem, volatile LAS unsigned* vb_) {
;     ...
; #pragma unroll
;     for (int i = 0; i < 8; ++i)
; #pragma unroll
;       for (int j = 0; j < 4; ++j)
; #pragma unroll
;         for (int r = 0; r < 4; ++r)
;           smem[(wm * 128 + i * 16 + (lane >> 4) * 4 + r) * 264 + wn * 64 + j * 16 + (lane & 15)] = f2bf(acc[i][j][r]);
;     __syncthreads();
;     const int tid2 = RTID;
; #pragma unroll
;     for (int k = 0; k < 16; ++k) {
;       const int c = tid2 + 512 * k;
;       const int row = c >> 5, ch = c & 31;
;       const uint4 v = *(const uint4*)(smem + row * 264 + ch * 8);
;       u16* d_ = (ch < 16) ? dstA : dstB;
;       const int l_ = (ch < 16) ? ldA : ldB;
;       *(uint4*)(d_ + (size_t)(mt * 256 + row) * l_ + (ch & 15) * 8) = v;
;     }
	v_and_b32_e32 v228, 15, v175
	v_bfe_u32 v229, v175, 8, 1
	v_lshl_or_b32 v228, v229, 7, v228
	v_mul_u32_u24_e32 v228, 0x210, v228
	v_bfe_u32 v229, v175, 6, 2
	v_lshl_add_u32 v228, v229, 7, v228
	v_bfe_u32 v229, v175, 4, 2
	v_lshl_add_u32 v228, v229, 3, v228
	v_cvt_pk_bf16_f32 v158, v158, v159
	v_cvt_pk_bf16_f32 v159, v160, v161
	v_cvt_pk_bf16_f32 v154, v154, v155
	v_cvt_pk_bf16_f32 v155, v156, v157
	v_cvt_pk_bf16_f32 v150, v150, v151
	v_cvt_pk_bf16_f32 v151, v152, v153
	v_cvt_pk_bf16_f32 v146, v146, v147
	v_cvt_pk_bf16_f32 v147, v148, v149
	ds_write_b64 v228, v[158:159]
	ds_write_b64 v228, v[154:155] offset:32
	ds_write_b64 v228, v[150:151] offset:64
	ds_write_b64 v228, v[146:147] offset:96
	v_cvt_pk_bf16_f32 v142, v142, v143
	v_cvt_pk_bf16_f32 v143, v144, v145
	v_cvt_pk_bf16_f32 v138, v138, v139
	v_cvt_pk_bf16_f32 v139, v140, v141
	v_cvt_pk_bf16_f32 v134, v134, v135
	v_cvt_pk_bf16_f32 v135, v136, v137
	v_cvt_pk_bf16_f32 v130, v130, v131
	v_cvt_pk_bf16_f32 v131, v132, v133
	ds_write_b64 v228, v[142:143] offset:8448
	ds_write_b64 v228, v[138:139] offset:8480
	ds_write_b64 v228, v[134:135] offset:8512
	ds_write_b64 v228, v[130:131] offset:8544
	v_cvt_pk_bf16_f32 v126, v126, v127
	v_cvt_pk_bf16_f32 v127, v128, v129
	v_cvt_pk_bf16_f32 v122, v122, v123
	v_cvt_pk_bf16_f32 v123, v124, v125
	v_cvt_pk_bf16_f32 v118, v118, v119
	v_cvt_pk_bf16_f32 v119, v120, v121
	v_cvt_pk_bf16_f32 v114, v114, v115
	v_cvt_pk_bf16_f32 v115, v116, v117
	ds_write_b64 v228, v[126:127] offset:16896
	ds_write_b64 v228, v[122:123] offset:16928
	ds_write_b64 v228, v[118:119] offset:16960
	ds_write_b64 v228, v[114:115] offset:16992
	v_cvt_pk_bf16_f32 v110, v110, v111
	v_cvt_pk_bf16_f32 v111, v112, v113
	v_cvt_pk_bf16_f32 v106, v106, v107
	v_cvt_pk_bf16_f32 v107, v108, v109
	v_cvt_pk_bf16_f32 v102, v102, v103
	v_cvt_pk_bf16_f32 v103, v104, v105
	v_cvt_pk_bf16_f32 v98, v98, v99
	v_cvt_pk_bf16_f32 v99, v100, v101
	ds_write_b64 v228, v[110:111] offset:25344
	ds_write_b64 v228, v[106:107] offset:25376
	ds_write_b64 v228, v[102:103] offset:25408
	ds_write_b64 v228, v[98:99] offset:25440
	v_cvt_pk_bf16_f32 v94, v94, v95
	v_cvt_pk_bf16_f32 v95, v96, v97
	v_cvt_pk_bf16_f32 v90, v90, v91
	v_cvt_pk_bf16_f32 v91, v92, v93
	v_cvt_pk_bf16_f32 v86, v86, v87
	v_cvt_pk_bf16_f32 v87, v88, v89
	v_cvt_pk_bf16_f32 v82, v82, v83
	v_cvt_pk_bf16_f32 v83, v84, v85
	ds_write_b64 v228, v[94:95] offset:33792
	ds_write_b64 v228, v[90:91] offset:33824
	ds_write_b64 v228, v[86:87] offset:33856
	ds_write_b64 v228, v[82:83] offset:33888
	v_cvt_pk_bf16_f32 v78, v78, v79
	v_cvt_pk_bf16_f32 v79, v80, v81
	v_cvt_pk_bf16_f32 v74, v74, v75
	v_cvt_pk_bf16_f32 v75, v76, v77
	v_cvt_pk_bf16_f32 v70, v70, v71
	v_cvt_pk_bf16_f32 v71, v72, v73
	v_cvt_pk_bf16_f32 v66, v66, v67
	v_cvt_pk_bf16_f32 v67, v68, v69
	ds_write_b64 v228, v[78:79] offset:42240
	ds_write_b64 v228, v[74:75] offset:42272
	ds_write_b64 v228, v[70:71] offset:42304
	ds_write_b64 v228, v[66:67] offset:42336
	v_cvt_pk_bf16_f32 v62, v62, v63
	v_cvt_pk_bf16_f32 v63, v64, v65
	v_cvt_pk_bf16_f32 v58, v58, v59
	v_cvt_pk_bf16_f32 v59, v60, v61
	v_cvt_pk_bf16_f32 v54, v54, v55
	v_cvt_pk_bf16_f32 v55, v56, v57
	v_cvt_pk_bf16_f32 v50, v50, v51
	v_cvt_pk_bf16_f32 v51, v52, v53
	ds_write_b64 v228, v[62:63] offset:50688
	ds_write_b64 v228, v[58:59] offset:50720
	ds_write_b64 v228, v[54:55] offset:50752
	ds_write_b64 v228, v[50:51] offset:50784
	v_cvt_pk_bf16_f32 v46, v46, v47
	v_cvt_pk_bf16_f32 v47, v48, v49
	v_cvt_pk_bf16_f32 v42, v42, v43
	v_cvt_pk_bf16_f32 v43, v44, v45
	v_cvt_pk_bf16_f32 v38, v38, v39
	v_cvt_pk_bf16_f32 v39, v40, v41
	v_cvt_pk_bf16_f32 v34, v34, v35
	v_cvt_pk_bf16_f32 v35, v36, v37
	ds_write_b64 v228, v[46:47] offset:59136
	ds_write_b64 v228, v[42:43] offset:59168
	ds_write_b64 v228, v[38:39] offset:59200
	ds_write_b64 v228, v[34:35] offset:59232
	v_mov_b32_e32 v43, v175
	s_waitcnt lgkmcnt(0)
	s_barrier
	global_load_dwordx4 v[98:101], v234, s[52:53] offset:128
	global_load_dwordx4 v[102:105], v235, s[52:53] offset:128
	global_load_dwordx4 v[106:109], v236, s[52:53] offset:128
	global_load_dwordx4 v[110:113], v237, s[52:53] offset:128
	global_load_dwordx4 v[114:117], v234, s[66:67] offset:128
	global_load_dwordx4 v[118:121], v235, s[66:67] offset:128
	global_load_dwordx4 v[122:125], v236, s[66:67] offset:128
	global_load_dwordx4 v[126:129], v237, s[66:67] offset:128
	global_load_dwordx4 v[130:133], v234, s[52:53] offset:256
	global_load_dwordx4 v[134:137], v235, s[52:53] offset:256
	global_load_dwordx4 v[138:141], v236, s[52:53] offset:256
	global_load_dwordx4 v[142:145], v237, s[52:53] offset:256
	global_load_dwordx4 v[146:149], v234, s[66:67] offset:256
	global_load_dwordx4 v[150:153], v235, s[66:67] offset:256
	global_load_dwordx4 v[154:157], v236, s[66:67] offset:256
	global_load_dwordx4 v[158:161], v237, s[66:67] offset:256
	s_mov_b32 s38, s36
	v_and_b32_e32 v0, 31, v43
	v_lshlrev_b32_e32 v42, 4, v0
	v_cmp_gt_u32_e32 vcc, 16, v0
	v_mov_b32_e32 v0, 0x100
	s_nop 0
	v_cndmask_b32_e64 v0, v0, 0, vcc
	v_lshl_add_u64 v[34:35], s[44:45], 0, v[0:1]
	v_lshlrev_b32_e32 v0, 4, v43
	v_and_b32_e32 v0, 0xf0, v0
	v_lshl_add_u64 v[44:45], v[34:35], 0, v[0:1]
	v_ashrrev_i32_e32 v0, 5, v43
	v_mad_u64_u32 v[34:35], s[12:13], v0, s2, v[42:43]
	v_add_u32_e32 v0, s10, v0
	ds_read_b128 v[34:37], v34
	v_ashrrev_i32_e32 v38, 31, v0
	v_mul_lo_u32 v40, s0, v38
	v_mul_lo_u32 v41, s1, v0
	v_mad_u64_u32 v[38:39], s[12:13], s0, v0, 0
	v_add_u32_e32 v0, 0x200, v43
	v_add3_u32 v39, v39, v40, v41
	v_ashrrev_i32_e32 v0, 5, v0
	v_lshl_add_u64 v[46:47], v[38:39], 1, v[44:45]
	v_mad_u64_u32 v[38:39], s[12:13], v0, s2, v[42:43]
	ds_read_b128 v[38:41], v38
	v_add_u32_e32 v0, s10, v0
	s_waitcnt lgkmcnt(1)
; __device__ __forceinline__ void phase_win(const Params& p, int part, u16* smem, volatile LAS unsigned* vb_) {
;     ...
; #pragma unroll
;     for (int k = 0; k < 16; ++k) {
;       const int c = tid2 + 512 * k;
;       const int row = c >> 5, ch = c & 31;
;       const uint4 v = *(const uint4*)(smem + row * 264 + ch * 8);
;       u16* d_ = (ch < 16) ? dstA : dstB;
;       const int l_ = (ch < 16) ? ldA : ldB;
;       *(uint4*)(d_ + (size_t)(mt * 256 + row) * l_ + (ch & 15) * 8) = v;
;     }
;     __syncthreads();
;   }
	global_store_dwordx4 v[46:47], v[34:37], off
	s_and_b64 vcc, exec, s[42:43]
	s_nop 0
	v_ashrrev_i32_e32 v34, 31, v0
	v_mul_lo_u32 v36, s0, v34
	v_mul_lo_u32 v37, s1, v0
	v_mad_u64_u32 v[34:35], s[12:13], s0, v0, 0
	v_add3_u32 v35, v35, v36, v37
	v_add_u32_e32 v0, 0x400, v43
	v_lshl_add_u64 v[34:35], v[34:35], 1, v[44:45]
	v_ashrrev_i32_e32 v0, 5, v0
	s_waitcnt lgkmcnt(0)
	global_store_dwordx4 v[34:35], v[38:41], off
	v_mad_u64_u32 v[34:35], s[12:13], v0, s2, v[42:43]
	v_add_u32_e32 v0, s10, v0
	ds_read_b128 v[34:37], v34
	v_ashrrev_i32_e32 v38, 31, v0
	v_mul_lo_u32 v40, s0, v38
	v_mul_lo_u32 v41, s1, v0
	v_mad_u64_u32 v[38:39], s[12:13], s0, v0, 0
	v_add_u32_e32 v0, 0x600, v43
	v_add3_u32 v39, v39, v40, v41
	v_ashrrev_i32_e32 v0, 5, v0
	v_lshl_add_u64 v[46:47], v[38:39], 1, v[44:45]
	v_mad_u64_u32 v[38:39], s[12:13], v0, s2, v[42:43]
	ds_read_b128 v[38:41], v38
	v_add_u32_e32 v0, s10, v0
	s_waitcnt lgkmcnt(1)
	global_store_dwordx4 v[46:47], v[34:37], off
	s_nop 1
	v_ashrrev_i32_e32 v34, 31, v0
	v_mul_lo_u32 v36, s0, v34
	v_mul_lo_u32 v37, s1, v0
	v_mad_u64_u32 v[34:35], s[12:13], s0, v0, 0
	v_add3_u32 v35, v35, v36, v37
	v_add_u32_e32 v0, 0x800, v43
	v_lshl_add_u64 v[34:35], v[34:35], 1, v[44:45]
	v_ashrrev_i32_e32 v0, 5, v0
	s_waitcnt lgkmcnt(0)
	global_store_dwordx4 v[34:35], v[38:41], off
	v_mad_u64_u32 v[34:35], s[12:13], v0, s2, v[42:43]
	v_add_u32_e32 v0, s10, v0
	ds_read_b128 v[34:37], v34
	v_ashrrev_i32_e32 v38, 31, v0
	v_mul_lo_u32 v40, s0, v38
	v_mul_lo_u32 v41, s1, v0
	v_mad_u64_u32 v[38:39], s[12:13], s0, v0, 0
	v_add_u32_e32 v0, 0xa00, v43
	v_add3_u32 v39, v39, v40, v41
	v_ashrrev_i32_e32 v0, 5, v0
	v_lshl_add_u64 v[46:47], v[38:39], 1, v[44:45]
	v_mad_u64_u32 v[38:39], s[12:13], v0, s2, v[42:43]
	ds_read_b128 v[38:41], v38
	v_add_u32_e32 v0, s10, v0
	s_waitcnt lgkmcnt(1)
	global_store_dwordx4 v[46:47], v[34:37], off
	s_nop 1
	v_ashrrev_i32_e32 v34, 31, v0
	v_mul_lo_u32 v36, s0, v34
	v_mul_lo_u32 v37, s1, v0
	v_mad_u64_u32 v[34:35], s[12:13], s0, v0, 0
	v_add3_u32 v35, v35, v36, v37
	v_add_u32_e32 v0, 0xc00, v43
	v_lshl_add_u64 v[34:35], v[34:35], 1, v[44:45]
	v_ashrrev_i32_e32 v0, 5, v0
	s_waitcnt lgkmcnt(0)
	global_store_dwordx4 v[34:35], v[38:41], off
	v_mad_u64_u32 v[34:35], s[12:13], v0, s2, v[42:43]
	v_add_u32_e32 v0, s10, v0
	ds_read_b128 v[34:37], v34
	v_ashrrev_i32_e32 v38, 31, v0
	v_mul_lo_u32 v40, s0, v38
	v_mul_lo_u32 v41, s1, v0
	v_mad_u64_u32 v[38:39], s[12:13], s0, v0, 0
	v_add_u32_e32 v0, 0xe00, v43
	v_add3_u32 v39, v39, v40, v41
	v_ashrrev_i32_e32 v0, 5, v0
	v_lshl_add_u64 v[46:47], v[38:39], 1, v[44:45]
	v_mad_u64_u32 v[38:39], s[12:13], v0, s2, v[42:43]
	ds_read_b128 v[38:41], v38
	v_add_u32_e32 v0, s10, v0
	s_waitcnt lgkmcnt(1)
	global_store_dwordx4 v[46:47], v[34:37], off
	s_nop 1
	v_ashrrev_i32_e32 v34, 31, v0
	v_mul_lo_u32 v36, s0, v34
	v_mul_lo_u32 v37, s1, v0
	v_mad_u64_u32 v[34:35], s[12:13], s0, v0, 0
	v_add3_u32 v35, v35, v36, v37
	v_add_u32_e32 v0, 0x1000, v43
	v_lshl_add_u64 v[34:35], v[34:35], 1, v[44:45]
	v_ashrrev_i32_e32 v0, 5, v0
	s_waitcnt lgkmcnt(0)
	global_store_dwordx4 v[34:35], v[38:41], off
	v_mad_u64_u32 v[34:35], s[12:13], v0, s2, v[42:43]
	v_add_u32_e32 v0, s10, v0
	ds_read_b128 v[34:37], v34
	v_ashrrev_i32_e32 v38, 31, v0
	v_mul_lo_u32 v40, s0, v38
	v_mul_lo_u32 v41, s1, v0
	v_mad_u64_u32 v[38:39], s[12:13], s0, v0, 0
	v_add_u32_e32 v0, 0x1200, v43
	v_add3_u32 v39, v39, v40, v41
	v_ashrrev_i32_e32 v0, 5, v0
	v_lshl_add_u64 v[46:47], v[38:39], 1, v[44:45]
	v_mad_u64_u32 v[38:39], s[12:13], v0, s2, v[42:43]
	ds_read_b128 v[38:41], v38
	v_add_u32_e32 v0, s10, v0
	s_waitcnt lgkmcnt(1)
	global_store_dwordx4 v[46:47], v[34:37], off
	s_nop 1
	v_ashrrev_i32_e32 v34, 31, v0
	v_mul_lo_u32 v36, s0, v34
	v_mul_lo_u32 v37, s1, v0
	v_mad_u64_u32 v[34:35], s[12:13], s0, v0, 0
	v_add3_u32 v35, v35, v36, v37
	v_add_u32_e32 v0, 0x1400, v43
	v_lshl_add_u64 v[34:35], v[34:35], 1, v[44:45]
	v_ashrrev_i32_e32 v0, 5, v0
	s_waitcnt lgkmcnt(0)
	global_store_dwordx4 v[34:35], v[38:41], off
	v_mad_u64_u32 v[34:35], s[12:13], v0, s2, v[42:43]
	v_add_u32_e32 v0, s10, v0
	ds_read_b128 v[34:37], v34
	v_ashrrev_i32_e32 v38, 31, v0
	v_mul_lo_u32 v40, s0, v38
	v_mul_lo_u32 v41, s1, v0
	v_mad_u64_u32 v[38:39], s[12:13], s0, v0, 0
	v_add_u32_e32 v0, 0x1600, v43
	v_add3_u32 v39, v39, v40, v41
	v_ashrrev_i32_e32 v0, 5, v0
	v_lshl_add_u64 v[46:47], v[38:39], 1, v[44:45]
	v_mad_u64_u32 v[38:39], s[12:13], v0, s2, v[42:43]
	ds_read_b128 v[38:41], v38
	v_add_u32_e32 v0, s10, v0
	s_waitcnt lgkmcnt(1)
	global_store_dwordx4 v[46:47], v[34:37], off
	s_nop 1
	v_ashrrev_i32_e32 v34, 31, v0
	v_mul_lo_u32 v36, s0, v34
	v_mul_lo_u32 v37, s1, v0
	v_mad_u64_u32 v[34:35], s[12:13], s0, v0, 0
	v_add3_u32 v35, v35, v36, v37
	v_add_u32_e32 v0, 0x1800, v43
	v_lshl_add_u64 v[34:35], v[34:35], 1, v[44:45]
	v_ashrrev_i32_e32 v0, 5, v0
	s_waitcnt lgkmcnt(0)
	global_store_dwordx4 v[34:35], v[38:41], off
	v_mad_u64_u32 v[34:35], s[12:13], v0, s2, v[42:43]
	v_add_u32_e32 v0, s10, v0
	ds_read_b128 v[34:37], v34
	v_ashrrev_i32_e32 v38, 31, v0
	v_mul_lo_u32 v40, s0, v38
	v_mul_lo_u32 v41, s1, v0
	v_mad_u64_u32 v[38:39], s[12:13], s0, v0, 0
	v_add_u32_e32 v0, 0x1a00, v43
	v_add3_u32 v39, v39, v40, v41
	v_ashrrev_i32_e32 v0, 5, v0
	v_lshl_add_u64 v[46:47], v[38:39], 1, v[44:45]
	v_mad_u64_u32 v[38:39], s[12:13], v0, s2, v[42:43]
	ds_read_b128 v[38:41], v38
	v_add_u32_e32 v0, s10, v0
	s_waitcnt lgkmcnt(1)
	global_store_dwordx4 v[46:47], v[34:37], off
	s_nop 1
	v_ashrrev_i32_e32 v34, 31, v0
	v_mul_lo_u32 v36, s0, v34
	v_mul_lo_u32 v37, s1, v0
	v_mad_u64_u32 v[34:35], s[12:13], s0, v0, 0
	v_add3_u32 v35, v35, v36, v37
	v_add_u32_e32 v0, 0x1c00, v43
	v_lshl_add_u64 v[34:35], v[34:35], 1, v[44:45]
	v_ashrrev_i32_e32 v0, 5, v0
	s_waitcnt lgkmcnt(0)
	global_store_dwordx4 v[34:35], v[38:41], off
	v_mad_u64_u32 v[34:35], s[12:13], v0, s2, v[42:43]
	v_add_u32_e32 v0, s10, v0
	ds_read_b128 v[34:37], v34
	v_ashrrev_i32_e32 v38, 31, v0
	v_mul_lo_u32 v40, s0, v38
	v_mul_lo_u32 v41, s1, v0
	v_mad_u64_u32 v[38:39], s[12:13], s0, v0, 0
	v_add_u32_e32 v0, 0x1e00, v43
	v_add3_u32 v39, v39, v40, v41
	v_ashrrev_i32_e32 v0, 5, v0
	v_lshl_add_u64 v[46:47], v[38:39], 1, v[44:45]
	v_mad_u64_u32 v[38:39], s[12:13], v0, s2, v[42:43]
	ds_read_b128 v[38:41], v38
	v_add_u32_e32 v0, s10, v0
	s_waitcnt lgkmcnt(1)
	global_store_dwordx4 v[46:47], v[34:37], off
	s_mov_b64 s[12:13], -1
	s_nop 0
	v_ashrrev_i32_e32 v34, 31, v0
	v_mul_lo_u32 v36, s0, v34
	v_mul_lo_u32 v37, s1, v0
	v_mad_u64_u32 v[34:35], s[0:1], s0, v0, 0
	v_add3_u32 v35, v35, v36, v37
	v_lshl_add_u64 v[34:35], v[34:35], 1, v[44:45]
	s_waitcnt lgkmcnt(0)
	global_store_dwordx4 v[34:35], v[38:41], off
	s_barrier
	s_cbranch_vccz .LBB0_441
